# stage A rank computation: all 13 LDS reads in one batch, compare results in rotating SGPR pairs accumulated by v_addc (2 VALU per candidate, no hazard nops)
# speedup vs baseline: 1.0081x; 1.0081x over previous
.LBB0_767:
	ds_read_b32 v2, v1
	ds_read_b32 v3, v0
	s_waitcnt lgkmcnt(1)
	v_and_b32_e32 v5, 0xffffff80, v2
	s_waitcnt lgkmcnt(0)
	v_and_b32_e32 v4, 0xffffff80, v3
	v_pk_add_f32 v[4:5], v[4:5], v[4:5] op_sel:[1,0] op_sel_hi:[0,1]
	v_and_b32_e32 v4, 0xffffffc0, v4
	v_bitop3_b32 v4, v4, 63, v175 bitop3:0x36
	v_cndmask_b32_e64 v22, v187, v4, s[0:1]
	ds_write_b32 v180, v22 offset:2048
	s_waitcnt lgkmcnt(0)
	ds_read_b128 v[194:197], v177 offset:2048
	ds_read_b128 v[198:201], v177 offset:2064
	ds_read_b128 v[202:205], v177 offset:2080
	ds_read_b128 v[206:209], v177 offset:2096
	ds_read_b128 v[210:213], v177 offset:2112
	ds_read_b128 v[214:217], v177 offset:2128
	ds_read_b128 v[218:221], v177 offset:2144
	ds_read_b128 v[222:225], v177 offset:2160
	ds_read_b128 v[226:229], v177 offset:2176
	ds_read_b128 v[230:233], v177 offset:2192
	ds_read_b128 v[234:237], v177 offset:2208
	ds_read_b128 v[238:241], v177 offset:2224
	ds_read_b128 v[4:7], v177 offset:2240
	v_mov_b32_e32 v10, 0
	s_waitcnt lgkmcnt(12)
	v_cmp_gt_f32_e64 s[90:91], v194, v22
	v_cmp_gt_f32_e64 s[92:93], v195, v22
	v_cmp_gt_f32_e64 s[94:95], v196, v22
	v_cmp_gt_f32_e64 s[96:97], v197, v22
	v_addc_co_u32_e64 v10, s[98:99], 0, v10, s[90:91]
	v_addc_co_u32_e64 v10, s[98:99], 0, v10, s[92:93]
	v_addc_co_u32_e64 v10, s[98:99], 0, v10, s[94:95]
	v_addc_co_u32_e64 v10, s[98:99], 0, v10, s[96:97]
	s_waitcnt lgkmcnt(11)
	v_cmp_gt_f32_e64 s[90:91], v198, v22
	v_cmp_gt_f32_e64 s[92:93], v199, v22
	v_cmp_gt_f32_e64 s[94:95], v200, v22
	v_cmp_gt_f32_e64 s[96:97], v201, v22
	v_addc_co_u32_e64 v10, s[98:99], 0, v10, s[90:91]
	v_addc_co_u32_e64 v10, s[98:99], 0, v10, s[92:93]
	v_addc_co_u32_e64 v10, s[98:99], 0, v10, s[94:95]
	v_addc_co_u32_e64 v10, s[98:99], 0, v10, s[96:97]
	s_waitcnt lgkmcnt(10)
	v_cmp_gt_f32_e64 s[90:91], v202, v22
	v_cmp_gt_f32_e64 s[92:93], v203, v22
	v_cmp_gt_f32_e64 s[94:95], v204, v22
	v_cmp_gt_f32_e64 s[96:97], v205, v22
	v_addc_co_u32_e64 v10, s[98:99], 0, v10, s[90:91]
	v_addc_co_u32_e64 v10, s[98:99], 0, v10, s[92:93]
	v_addc_co_u32_e64 v10, s[98:99], 0, v10, s[94:95]
	v_addc_co_u32_e64 v10, s[98:99], 0, v10, s[96:97]
	s_waitcnt lgkmcnt(9)
	v_cmp_gt_f32_e64 s[90:91], v206, v22
	v_cmp_gt_f32_e64 s[92:93], v207, v22
	v_cmp_gt_f32_e64 s[94:95], v208, v22
	v_cmp_gt_f32_e64 s[96:97], v209, v22
	v_addc_co_u32_e64 v10, s[98:99], 0, v10, s[90:91]
	v_addc_co_u32_e64 v10, s[98:99], 0, v10, s[92:93]
	v_addc_co_u32_e64 v10, s[98:99], 0, v10, s[94:95]
	v_addc_co_u32_e64 v10, s[98:99], 0, v10, s[96:97]
	s_waitcnt lgkmcnt(8)
	v_cmp_gt_f32_e64 s[90:91], v210, v22
	v_cmp_gt_f32_e64 s[92:93], v211, v22
	v_cmp_gt_f32_e64 s[94:95], v212, v22
	v_cmp_gt_f32_e64 s[96:97], v213, v22
	v_addc_co_u32_e64 v10, s[98:99], 0, v10, s[90:91]
	v_addc_co_u32_e64 v10, s[98:99], 0, v10, s[92:93]
	v_addc_co_u32_e64 v10, s[98:99], 0, v10, s[94:95]
	v_addc_co_u32_e64 v10, s[98:99], 0, v10, s[96:97]
	s_waitcnt lgkmcnt(7)
	v_cmp_gt_f32_e64 s[90:91], v214, v22
	v_cmp_gt_f32_e64 s[92:93], v215, v22
	v_cmp_gt_f32_e64 s[94:95], v216, v22
	v_cmp_gt_f32_e64 s[96:97], v217, v22
	v_addc_co_u32_e64 v10, s[98:99], 0, v10, s[90:91]
	v_addc_co_u32_e64 v10, s[98:99], 0, v10, s[92:93]
	v_addc_co_u32_e64 v10, s[98:99], 0, v10, s[94:95]
	v_addc_co_u32_e64 v10, s[98:99], 0, v10, s[96:97]
	s_waitcnt lgkmcnt(6)
	v_cmp_gt_f32_e64 s[90:91], v218, v22
	v_cmp_gt_f32_e64 s[92:93], v219, v22
	v_cmp_gt_f32_e64 s[94:95], v220, v22
	v_cmp_gt_f32_e64 s[96:97], v221, v22
	v_addc_co_u32_e64 v10, s[98:99], 0, v10, s[90:91]
	v_addc_co_u32_e64 v10, s[98:99], 0, v10, s[92:93]
	v_addc_co_u32_e64 v10, s[98:99], 0, v10, s[94:95]
	v_addc_co_u32_e64 v10, s[98:99], 0, v10, s[96:97]
	s_waitcnt lgkmcnt(5)
	v_cmp_gt_f32_e64 s[90:91], v222, v22
	v_cmp_gt_f32_e64 s[92:93], v223, v22
	v_cmp_gt_f32_e64 s[94:95], v224, v22
	v_cmp_gt_f32_e64 s[96:97], v225, v22
	v_addc_co_u32_e64 v10, s[98:99], 0, v10, s[90:91]
	v_addc_co_u32_e64 v10, s[98:99], 0, v10, s[92:93]
	v_addc_co_u32_e64 v10, s[98:99], 0, v10, s[94:95]
	v_addc_co_u32_e64 v10, s[98:99], 0, v10, s[96:97]
	s_waitcnt lgkmcnt(4)
	v_cmp_gt_f32_e64 s[90:91], v226, v22
	v_cmp_gt_f32_e64 s[92:93], v227, v22
	v_cmp_gt_f32_e64 s[94:95], v228, v22
	v_cmp_gt_f32_e64 s[96:97], v229, v22
	v_addc_co_u32_e64 v10, s[98:99], 0, v10, s[90:91]
	v_addc_co_u32_e64 v10, s[98:99], 0, v10, s[92:93]
	v_addc_co_u32_e64 v10, s[98:99], 0, v10, s[94:95]
	v_addc_co_u32_e64 v10, s[98:99], 0, v10, s[96:97]
	s_waitcnt lgkmcnt(3)
	v_cmp_gt_f32_e64 s[90:91], v230, v22
	v_cmp_gt_f32_e64 s[92:93], v231, v22
	v_cmp_gt_f32_e64 s[94:95], v232, v22
	v_cmp_gt_f32_e64 s[96:97], v233, v22
	v_addc_co_u32_e64 v10, s[98:99], 0, v10, s[90:91]
	v_addc_co_u32_e64 v10, s[98:99], 0, v10, s[92:93]
	v_addc_co_u32_e64 v10, s[98:99], 0, v10, s[94:95]
	v_addc_co_u32_e64 v10, s[98:99], 0, v10, s[96:97]
	s_waitcnt lgkmcnt(2)
	v_cmp_gt_f32_e64 s[90:91], v234, v22
	v_cmp_gt_f32_e64 s[92:93], v235, v22
	v_cmp_gt_f32_e64 s[94:95], v236, v22
	v_cmp_gt_f32_e64 s[96:97], v237, v22
	v_addc_co_u32_e64 v10, s[98:99], 0, v10, s[90:91]
	v_addc_co_u32_e64 v10, s[98:99], 0, v10, s[92:93]
	v_addc_co_u32_e64 v10, s[98:99], 0, v10, s[94:95]
	v_addc_co_u32_e64 v10, s[98:99], 0, v10, s[96:97]
	s_waitcnt lgkmcnt(1)
	v_cmp_gt_f32_e64 s[90:91], v238, v22
	v_cmp_gt_f32_e64 s[92:93], v239, v22
	v_cmp_gt_f32_e64 s[94:95], v240, v22
	v_cmp_gt_f32_e64 s[96:97], v241, v22
	v_addc_co_u32_e64 v10, s[98:99], 0, v10, s[90:91]
	v_addc_co_u32_e64 v10, s[98:99], 0, v10, s[92:93]
	v_addc_co_u32_e64 v10, s[98:99], 0, v10, s[94:95]
	v_addc_co_u32_e64 v10, s[98:99], 0, v10, s[96:97]
	s_waitcnt lgkmcnt(0)
	v_cmp_gt_f32_e64 s[90:91], v4, v22
	v_cmp_gt_f32_e64 s[92:93], v5, v22
	s_nop 1
	v_addc_co_u32_e64 v10, s[98:99], 0, v10, s[90:91]
	v_addc_co_u32_e64 v10, s[98:99], 0, v10, s[92:93]
	v_mov_b32_e32 v5, v10
	v_mov_b32_e32 v4, 0
	v_max_f32_e32 v10, v22, v22
	v_cmp_gt_f32_e32 vcc, v6, v22
	v_mov_b32_dpp v4, v22 quad_perm:[1,0,3,2] row_mask:0xf bank_mask:0xf
	v_max_f32_e32 v4, v4, v4
	v_max_f32_e32 v4, v10, v4
	v_mov_b32_e32 v10, 0
	v_cndmask_b32_e64 v6, 0, 1, vcc
	v_cmp_gt_f32_e32 vcc, v7, v22
	v_mov_b32_dpp v10, v4 quad_perm:[2,3,0,1] row_mask:0xf bank_mask:0xf
	v_max_f32_e32 v10, v10, v10
	v_max_f32_e32 v4, v4, v10
	v_mov_b32_e32 v10, 0
	v_addc_co_u32_e32 v5, vcc, v5, v6, vcc
	s_nop 0
	v_mov_b32_dpp v10, v4 row_half_mirror row_mask:0xf bank_mask:0xf
	v_max_f32_e32 v10, v10, v10
	v_max_f32_e32 v4, v4, v10
	v_mov_b32_e32 v10, 0
	v_cmp_gt_u32_e32 vcc, 16, v5
	s_and_b64 vcc, s[0:1], vcc
	v_mov_b32_dpp v10, v4 row_mirror row_mask:0xf bank_mask:0xf
	v_max_f32_e32 v10, v10, v10
	v_max_f32_e32 v4, v4, v10
	v_mov_b32_e32 v10, v4
	s_nop 1
	v_permlane16_swap_b32_e32 v4, v10
	v_max_f32_e32 v10, v10, v10
	v_max_f32_e32 v4, v4, v4
	v_max_f32_e32 v4, v4, v10
	v_mov_b32_e32 v10, v4
	s_nop 1
	v_permlane32_swap_b32_e32 v4, v10
	v_max_f32_e32 v10, v10, v10
	v_max_f32_e32 v4, v4, v4
	v_max_f32_e32 v4, v4, v10
	v_sub_f32_e32 v4, v22, v4
	v_mul_f32_e32 v4, 0x3fb8aa3b, v4
	v_exp_f32_e32 v4, v4
	s_nop 0
	v_cndmask_b32_e32 v6, 0, v4, vcc
	s_nop 1
	v_add_f32_dpp v6, v6, v6 quad_perm:[1,0,3,2] row_mask:0xf bank_mask:0xf bound_ctrl:1
	s_nop 1
	v_add_f32_dpp v6, v6, v6 quad_perm:[2,3,0,1] row_mask:0xf bank_mask:0xf bound_ctrl:1
	s_nop 1
	v_add_f32_dpp v6, v6, v6 row_half_mirror row_mask:0xf bank_mask:0xf bound_ctrl:1
	s_nop 1
	v_add_f32_dpp v6, v6, v6 row_mirror row_mask:0xf bank_mask:0xf bound_ctrl:1
	v_mov_b32_e32 v7, v6
	s_nop 1
	v_permlane16_swap_b32_e32 v6, v7
	v_add_f32_e32 v6, v6, v7
	v_mov_b32_e32 v7, v6
	s_nop 1
	v_permlane32_swap_b32_e32 v6, v7
	s_and_saveexec_b64 s[6:7], vcc
	s_cbranch_execz .LBB0_766
	v_add_f32_e32 v6, v6, v7
	v_div_scale_f32 v7, s[10:11], v6, v6, v4
	v_rcp_f32_e32 v10, v7
	v_lshlrev_b32_e32 v3, 7, v3
	v_and_b32_e32 v2, 0x7f, v2
	v_and_or_b32 v2, v3, s61, v2
	v_add_u32_e32 v3, s8, v5
	v_fma_f32 v5, -v7, v10, 1.0
	v_fmac_f32_e32 v10, v5, v10
	v_div_scale_f32 v5, vcc, v4, v6, v4
	v_mul_f32_e32 v11, v5, v10
	v_fma_f32 v12, -v7, v11, v5
	v_fmac_f32_e32 v11, v12, v10
	v_fma_f32 v5, -v7, v11, v5
	v_div_fmas_f32 v5, v5, v10, v11
	v_lshl_add_u32 v3, v3, 2, v177
	v_div_fixup_f32 v4, v5, v6, v4
	ds_write2st64_b32 v3, v2, v4 offset0:4 offset1:6
	s_branch .LBB0_766
